# xattn: s_waitcnt vmcnt(0) added late in the QK MFMA cluster (wave stagger experiment, mirrors E4's in-cluster waits) on v6
# baseline (speedup 1.0000x reference)
; #define LAS __attribute__((address_space(3)))
; template <int DQK, int DV, int MODE, bool QNORM, int SK, int NQ> ...
;     ...
;         LAS unsigned char* sb = lds + (sg & 1) * STAGE;
;         if (NSUB * sg < nst_w) {
;             f32x16 sc[NQ][NSUB];
; #pragma unroll
;             for (int qh = 0; qh < NQ; ++qh)
; #pragma unroll
;                 for (int sub = 0; sub < NSUB; ++sub)
; #pragma unroll
;                     for (int r = 0; r < 16; ++r) sc[qh][sub][r] = QNORM ? 0.f : -m_run[qh];
;             if (NQ == 1 && DQK <= 96) {
;                 bf16x8 kfa[NSUB][DQK / 16];
; #pragma unroll
;                 for (int d0 = 0; d0 < DQK / 16; ++d0)
; #pragma unroll
;                     for (int sub = 0; sub < NSUB; ++sub) kfa[sub][d0] = *(const LAS bf16x8*)(sb + (sub * 32 + r32) * KP + hi * 16 + d0 * 32);
;                 asm volatile("s_waitcnt lgkmcnt(0)" ::: "memory");
;                 __builtin_amdgcn_sched_barrier(0);
;                 __builtin_amdgcn_s_setprio(1);
; #pragma unroll
;                 for (int d0 = 0; d0 < DQK / 16; ++d0)
; #pragma unroll
;                     for (int sub = 0; sub < NSUB; ++sub) sc[0][sub] = __builtin_amdgcn_mfma_f32_32x32x16_bf16(kfa[sub][d0], qf[0][d0], sc[0][sub], 0, 0, 0);
;             } else {
;             __builtin_amdgcn_s_setprio(1);
; #pragma unroll
;             for (int d0 = 0; d0 < DQK / 16; ++d0)
; #pragma unroll
;                 for (int sub = 0; sub < NSUB; ++sub) {
;                     const bf16x8 kf = *(const LAS bf16x8*)(sb + (sub * 32 + r32) * KP + hi * 16 + d0 * 32);
; #pragma unroll
;                     for (int qh = 0; qh < NQ; ++qh) sc[qh][sub] = __builtin_amdgcn_mfma_f32_32x32x16_bf16(kf, qf[qh][d0], sc[qh][sub], 0, 0, 0);
;                 }
;             }
;             __builtin_amdgcn_s_setprio(0);
;     ...
;                 float tm = sc[qh][0][0];
; #pragma unroll
;                 for (int sub = 0; sub < NSUB; ++sub)
; #pragma unroll
;                     for (int r = 0; r < 16; ++r) tm = fmaxf(tm, sc[qh][sub][r]);
;                 tm = fmaxf(tm, __shfl_xor(tm, 32));
;                 if (__ballot(tm > 0.f) != 0ull) {
;                     const float dl = fmaxf(tm, 0.f); m_run[qh] += dl;
;                     const float alpha = __builtin_amdgcn_exp2f(-dl);
;                     l_run[qh] *= alpha;
; #pragma unroll
;                     for (int sub = 0; sub < NSUB; ++sub)
; #pragma unroll
.LBB0_4653:
	s_or_b64 exec, exec, s[12:13]
	s_bitcmp1_b32 s15, 0
	s_cselect_b32 s12, 0x6a00, 0
	s_add_i32 s12, s12, 0
	s_setprio 1
	v_add3_u32 v1, s12, v180, v181
	ds_read_b128 v[66:69], v1
	ds_read_b128 v[192:195], v1 offset:32
	s_waitcnt lgkmcnt(1)
	v_mfma_f32_32x32x16_bf16 v[66:81], v[66:69], v[142:145], 0
	s_waitcnt lgkmcnt(0)
	v_mfma_f32_32x32x16_bf16 v[66:81], v[192:195], v[138:141], v[66:81]
	ds_read_b128 v[192:195], v1 offset:64
	s_waitcnt lgkmcnt(0)
	v_mfma_f32_32x32x16_bf16 v[66:81], v[192:195], v[134:137], v[66:81]
	ds_read_b128 v[192:195], v1 offset:96
	s_waitcnt lgkmcnt(0)
	v_mfma_f32_32x32x16_bf16 v[66:81], v[192:195], v[126:129], v[66:81]
	ds_read_b128 v[192:195], v1 offset:128
	s_waitcnt lgkmcnt(0)
	v_mfma_f32_32x32x16_bf16 v[66:81], v[192:195], v[118:121], v[66:81]
	ds_read_b128 v[192:195], v1 offset:160
	s_waitcnt lgkmcnt(0)
	v_mfma_f32_32x32x16_bf16 v[66:81], v[192:195], v[110:113], v[66:81]
	ds_read_b128 v[192:195], v1 offset:192
	s_waitcnt lgkmcnt(0)
	v_mfma_f32_32x32x16_bf16 v[66:81], v[192:195], v[102:105], v[66:81]
	ds_read_b128 v[192:195], v1 offset:224
	s_waitcnt lgkmcnt(0)
	v_mfma_f32_32x32x16_bf16 v[66:81], v[192:195], v[130:133], v[66:81]
	ds_read_b128 v[192:195], v1 offset:256
	s_waitcnt lgkmcnt(0)
	v_mfma_f32_32x32x16_bf16 v[66:81], v[192:195], v[122:125], v[66:81]
	ds_read_b128 v[192:195], v1 offset:288
	s_waitcnt lgkmcnt(0)
	v_mfma_f32_32x32x16_bf16 v[66:81], v[192:195], v[114:117], v[66:81]
	ds_read_b128 v[192:195], v1 offset:320
	s_waitcnt lgkmcnt(0)
	v_mfma_f32_32x32x16_bf16 v[66:81], v[192:195], v[106:109], v[66:81]
	ds_read_b128 v[192:195], v1 offset:352
	s_waitcnt lgkmcnt(0)
	v_mfma_f32_32x32x16_bf16 v[66:81], v[192:195], v[98:101], v[66:81]
	ds_read_b128 v[192:195], v1 offset:384
	s_waitcnt lgkmcnt(0)
	v_mfma_f32_32x32x16_bf16 v[66:81], v[192:195], v[94:97], v[66:81]
	ds_read_b128 v[192:195], v1 offset:416
	s_waitcnt lgkmcnt(0)
	v_mfma_f32_32x32x16_bf16 v[66:81], v[192:195], v[90:93], v[66:81]
	ds_read_b128 v[192:195], v1 offset:448
	s_waitcnt lgkmcnt(0)
	s_waitcnt vmcnt(0)
	v_mfma_f32_32x32x16_bf16 v[66:81], v[192:195], v[86:89], v[66:81]
	ds_read_b128 v[192:195], v1 offset:480
	s_waitcnt lgkmcnt(0)
	v_mfma_f32_32x32x16_bf16 v[66:81], v[192:195], v[82:85], v[66:81]
	s_setprio 0
	s_nop 10
	v_pk_fma_f32 v[66:67], v[170:171], v[66:67], v[172:173] op_sel_hi:[1,1,0] neg_lo:[0,0,1] neg_hi:[0,0,1]
	v_pk_fma_f32 v[68:69], v[170:171], v[68:69], v[172:173] op_sel_hi:[1,1,0] neg_lo:[0,0,1] neg_hi:[0,0,1]
	v_max_f32_e32 v1, v66, v67
	v_pk_fma_f32 v[70:71], v[170:171], v[70:71], v[172:173] op_sel_hi:[1,1,0] neg_lo:[0,0,1] neg_hi:[0,0,1]
	v_max3_f32 v1, v1, v68, v69
	v_pk_fma_f32 v[72:73], v[170:171], v[72:73], v[172:173] op_sel_hi:[1,1,0] neg_lo:[0,0,1] neg_hi:[0,0,1]
	v_max3_f32 v1, v1, v70, v71
	v_pk_fma_f32 v[74:75], v[170:171], v[74:75], v[172:173] op_sel_hi:[1,1,0] neg_lo:[0,0,1] neg_hi:[0,0,1]
	v_max3_f32 v1, v1, v72, v73
	v_pk_fma_f32 v[76:77], v[170:171], v[76:77], v[172:173] op_sel_hi:[1,1,0] neg_lo:[0,0,1] neg_hi:[0,0,1]
	v_max3_f32 v1, v1, v74, v75
	v_pk_fma_f32 v[78:79], v[170:171], v[78:79], v[172:173] op_sel_hi:[1,1,0] neg_lo:[0,0,1] neg_hi:[0,0,1]
	v_max3_f32 v1, v1, v76, v77
	v_pk_fma_f32 v[80:81], v[170:171], v[80:81], v[172:173] op_sel_hi:[1,1,0] neg_lo:[0,0,1] neg_hi:[0,0,1]
	v_max3_f32 v1, v1, v78, v79
	v_max3_f32 v1, v1, v80, v81
	ds_bpermute_b32 v167, v222, v1
	s_waitcnt lgkmcnt(0)
	v_max_f32_e32 v167, v167, v167
	v_max_f32_e32 v1, v1, v167
	v_cmp_lt_f32_e32 vcc, 0, v1
	s_cbranch_vccz .LBB0_4655
	v_max_f32_e32 v1, v1, v1
	v_max_f32_e32 v192, 0, v1
	v_exp_f32_e64 v194, -v192
	v_pk_add_f32 v[66:67], v[66:67], v[192:193] op_sel_hi:[1,0] neg_lo:[0,1] neg_hi:[0,1]
	v_pk_add_f32 v[68:69], v[68:69], v[192:193] op_sel_hi:[1,0] neg_lo:[0,1] neg_hi:[0,1]
	v_pk_add_f32 v[70:71], v[70:71], v[192:193] op_sel_hi:[1,0] neg_lo:[0,1] neg_hi:[0,1]
	v_pk_add_f32 v[72:73], v[72:73], v[192:193] op_sel_hi:[1,0] neg_lo:[0,1] neg_hi:[0,1]
	v_pk_add_f32 v[74:75], v[74:75], v[192:193] op_sel_hi:[1,0] neg_lo:[0,1] neg_hi:[0,1]
	v_pk_add_f32 v[76:77], v[76:77], v[192:193] op_sel_hi:[1,0] neg_lo:[0,1] neg_hi:[0,1]
	v_pk_add_f32 v[78:79], v[78:79], v[192:193] op_sel_hi:[1,0] neg_lo:[0,1] neg_hi:[0,1]
	v_pk_add_f32 v[80:81], v[80:81], v[192:193] op_sel_hi:[1,0] neg_lo:[0,1] neg_hi:[0,1]
	v_add_f32_e32 v172, v172, v192
	v_pk_mul_f32 v[64:65], v[64:65], v[194:195] op_sel_hi:[1,0]
	v_pk_mul_f32 v[62:63], v[62:63], v[194:195] op_sel_hi:[1,0]
	v_pk_mul_f32 v[60:61], v[60:61], v[194:195] op_sel_hi:[1,0]
	v_pk_mul_f32 v[58:59], v[58:59], v[194:195] op_sel_hi:[1,0]
	v_pk_mul_f32 v[56:57], v[56:57], v[194:195] op_sel_hi:[1,0]
	v_pk_mul_f32 v[54:55], v[54:55], v[194:195] op_sel_hi:[1,0]
	v_pk_mul_f32 v[52:53], v[52:53], v[194:195] op_sel_hi:[1,0]
	v_pk_mul_f32 v[50:51], v[50:51], v[194:195] op_sel_hi:[1,0]
	v_pk_mul_f32 v[48:49], v[48:49], v[194:195] op_sel_hi:[1,0]
	v_pk_mul_f32 v[46:47], v[46:47], v[194:195] op_sel_hi:[1,0]
	v_pk_mul_f32 v[44:45], v[44:45], v[194:195] op_sel_hi:[1,0]
	v_pk_mul_f32 v[42:43], v[42:43], v[194:195] op_sel_hi:[1,0]
	v_pk_mul_f32 v[40:41], v[40:41], v[194:195] op_sel_hi:[1,0]
	v_pk_mul_f32 v[38:39], v[38:39], v[194:195] op_sel_hi:[1,0]
	v_pk_mul_f32 v[36:37], v[36:37], v[194:195] op_sel_hi:[1,0]
	v_pk_mul_f32 v[34:35], v[34:35], v[194:195] op_sel_hi:[1,0]
	v_pk_mul_f32 v[32:33], v[32:33], v[194:195] op_sel_hi:[1,0]
	v_pk_mul_f32 v[30:31], v[30:31], v[194:195] op_sel_hi:[1,0]
	v_pk_mul_f32 v[28:29], v[28:29], v[194:195] op_sel_hi:[1,0]
	v_pk_mul_f32 v[26:27], v[26:27], v[194:195] op_sel_hi:[1,0]
	v_pk_mul_f32 v[24:25], v[24:25], v[194:195] op_sel_hi:[1,0]
	v_pk_mul_f32 v[22:23], v[22:23], v[194:195] op_sel_hi:[1,0]
	v_pk_mul_f32 v[20:21], v[20:21], v[194:195] op_sel_hi:[1,0]
	v_pk_mul_f32 v[18:19], v[18:19], v[194:195] op_sel_hi:[1,0]
	v_pk_mul_f32 v[16:17], v[16:17], v[194:195] op_sel_hi:[1,0]
	v_pk_mul_f32 v[14:15], v[14:15], v[194:195] op_sel_hi:[1,0]
	v_pk_mul_f32 v[12:13], v[12:13], v[194:195] op_sel_hi:[1,0]
	v_pk_mul_f32 v[10:11], v[10:11], v[194:195] op_sel_hi:[1,0]
	v_pk_mul_f32 v[8:9], v[8:9], v[194:195] op_sel_hi:[1,0]
	v_pk_mul_f32 v[6:7], v[6:7], v[194:195] op_sel_hi:[1,0]
	v_pk_mul_f32 v[4:5], v[4:5], v[194:195] op_sel_hi:[1,0]
	v_pk_mul_f32 v[2:3], v[2:3], v[194:195] op_sel_hi:[1,0]
	v_mul_f32_e32 v165, v165, v194
